# P0 adaLN GEMV weight loop: next iteration's first four row loads issued together with the current iteration's eight (12 loads in flight, one exposed round trip per iteration instead of two); on top of
# baseline (speedup 1.0000x reference)
.LBB0_27:
	s_mul_hi_i32 s0, s71, 0x2aaaaaab
	s_lshr_b32 s1, s0, 31
	s_ashr_i32 s72, s0, 4
	s_add_i32 s72, s72, s1
	s_lshl_b32 s2, s72, 9
	v_or_b32_e32 v2, s2, v0
	v_ashrrev_i32_e32 v3, 31, v2
	v_lshl_add_u64 v[4:5], v[2:3], 2, s[22:23]
	s_mov_b64 s[0:1], 0
	v_mov_b32_e32 v6, v1
	v_mov_b32_e32 v7, v0
	v_lshlrev_b32_e32 v205, 2, v2
	v_add_u32_e32 v206, 0x4000, v205
	v_add_u32_e32 v207, 0x8000, v205
	v_add_u32_e32 v208, 0xc000, v205
	global_load_dword v200, v205, s[18:19]
	global_load_dword v201, v206, s[18:19]
	global_load_dword v202, v207, s[18:19]
	global_load_dword v203, v208, s[18:19]
	global_load_dword v204, v205, s[22:23]
	s_waitcnt vmcnt(0)
	v_mul_f32_e32 v8, 0xbfb8aa3b, v200
	v_exp_f32_e32 v8, v8
	s_nop 0
	v_add_f32_e32 v8, 1.0, v8
	v_div_scale_f32 v9, s[4:5], v8, v8, v200
	v_rcp_f32_e32 v10, v9
	v_div_scale_f32 v11, vcc, v200, v8, v200
	v_fma_f32 v12, -v9, v10, 1.0
	v_fmac_f32_e32 v10, v12, v10
	v_mul_f32_e32 v12, v11, v10
	v_fma_f32 v13, -v9, v12, v11
	v_fmac_f32_e32 v12, v13, v10
	v_fma_f32 v9, -v9, v12, v11
	v_div_fmas_f32 v9, v9, v10, v12
	v_div_fixup_f32 v200, v9, v8, v200
	ds_write_b32 v6, v200
	v_mul_f32_e32 v8, 0xbfb8aa3b, v201
	v_exp_f32_e32 v8, v8
	s_nop 0
	v_add_f32_e32 v8, 1.0, v8
	v_div_scale_f32 v9, s[4:5], v8, v8, v201
	v_rcp_f32_e32 v10, v9
	v_div_scale_f32 v11, vcc, v201, v8, v201
	v_fma_f32 v12, -v9, v10, 1.0
	v_fmac_f32_e32 v10, v12, v10
	v_mul_f32_e32 v12, v11, v10
	v_fma_f32 v13, -v9, v12, v11
	v_fmac_f32_e32 v12, v13, v10
	v_fma_f32 v9, -v9, v12, v11
	v_div_fmas_f32 v9, v9, v10, v12
	v_div_fixup_f32 v201, v9, v8, v201
	ds_write_b32 v6, v201 offset:2048
	v_mul_f32_e32 v8, 0xbfb8aa3b, v202
	v_exp_f32_e32 v8, v8
	s_nop 0
	v_add_f32_e32 v8, 1.0, v8
	v_div_scale_f32 v9, s[4:5], v8, v8, v202
	v_rcp_f32_e32 v10, v9
	v_div_scale_f32 v11, vcc, v202, v8, v202
	v_fma_f32 v12, -v9, v10, 1.0
	v_fmac_f32_e32 v10, v12, v10
	v_mul_f32_e32 v12, v11, v10
	v_fma_f32 v13, -v9, v12, v11
	v_fmac_f32_e32 v12, v13, v10
	v_fma_f32 v9, -v9, v12, v11
	v_div_fmas_f32 v9, v9, v10, v12
	v_div_fixup_f32 v202, v9, v8, v202
	ds_write_b32 v6, v202 offset:4096
	v_mul_f32_e32 v8, 0xbfb8aa3b, v203
	v_exp_f32_e32 v8, v8
	s_nop 0
	v_add_f32_e32 v8, 1.0, v8
	v_div_scale_f32 v9, s[4:5], v8, v8, v203
	v_rcp_f32_e32 v10, v9
	v_div_scale_f32 v11, vcc, v203, v8, v203
	v_fma_f32 v12, -v9, v10, 1.0
	v_fmac_f32_e32 v10, v12, v10
	v_mul_f32_e32 v12, v11, v10
	v_fma_f32 v13, -v9, v12, v11
	v_fmac_f32_e32 v12, v13, v10
	v_fma_f32 v9, -v9, v12, v11
	v_div_fmas_f32 v9, v9, v10, v12
	v_div_fixup_f32 v203, v9, v8, v203
	ds_write_b32 v6, v203 offset:6144
	v_mul_f32_e32 v8, 0xbfb8aa3b, v204
	v_exp_f32_e32 v8, v8
	s_nop 0
	v_add_f32_e32 v8, 1.0, v8
	v_div_scale_f32 v9, s[4:5], v8, v8, v204
	v_rcp_f32_e32 v10, v9
	v_div_scale_f32 v11, vcc, v204, v8, v204
	v_fma_f32 v12, -v9, v10, 1.0
	v_fmac_f32_e32 v10, v12, v10
	v_mul_f32_e32 v12, v11, v10
	v_fma_f32 v13, -v9, v12, v11
	v_fmac_f32_e32 v12, v13, v10
	v_fma_f32 v9, -v9, v12, v11
	v_div_fmas_f32 v9, v9, v10, v12
	v_div_fixup_f32 v204, v9, v8, v204
	ds_write_b32 v6, v204 offset:8192
	v_mov_b32_e32 v3, v204
	v_add_u32_e32 v2, 0x5000, v2
	v_add_u32_e32 v6, 0x2800, v6
	v_add_u32_e32 v7, 0xa00, v7
	s_or_b64 exec, exec, s[0:1]
	v_readfirstlane_b32 s4, v55
	s_mul_i32 s0, s72, 0x60
	s_add_i32 s1, s4, s2
	s_sub_i32 s0, s71, s0
	s_mul_hi_i32 s2, s1, 0x18000
	s_mul_i32 s1, s1, 0x18000
	s_add_u32 s5, s24, s1
	s_addc_u32 s73, s25, s2
	s_lshl_b32 s0, s0, 8
	s_ashr_i32 s1, s0, 31
	s_lshl_b64 s[2:3], s[0:1], 2
	s_add_u32 s2, s5, s2
	s_addc_u32 s3, s73, s3
	s_lshl_b32 s1, s4, 2
	v_mov_b32_e32 v22, 0
	v_lshl_add_u64 v[30:31], s[2:3], 0, v[28:29]
	s_add_i32 s1, s1, 0
	s_mov_b64 s[2:3], 0
	v_mov_b32_e32 v23, v22
	v_mov_b32_e32 v24, v22
	v_mov_b32_e32 v25, v22
	v_mov_b32_e32 v42, v22
	v_mov_b32_e32 v43, v22
	v_mov_b32_e32 v36, v22
	v_mov_b32_e32 v37, v22
	v_mov_b32_e32 v46, v22
	v_mov_b32_e32 v47, v22
	v_mov_b32_e32 v38, v22
	v_mov_b32_e32 v39, v22
	v_mov_b32_e32 v48, v22
	v_mov_b32_e32 v49, v22
	v_mov_b32_e32 v40, v22
	v_mov_b32_e32 v41, v22
	v_mov_b32_e32 v50, v22
	v_mov_b32_e32 v51, v22
	v_mov_b32_e32 v44, v22
	v_mov_b32_e32 v45, v22
	s_waitcnt lgkmcnt(0)
	v_lshl_add_u64 v[126:127], v[30:31], 0, s[2:3]
	global_load_dwordx4 v[110:113], v[126:127], off nt
	s_mov_b32 s101, 0
	s_mov_b32 s100, s35
	v_lshl_add_u64 v[128:129], v[126:127], 0, s[100:101]
	global_load_dwordx4 v[114:117], v[128:129], off nt
	s_mov_b32 s100, s57
	v_lshl_add_u64 v[128:129], v[126:127], 0, s[100:101]
	global_load_dwordx4 v[118:121], v[128:129], off nt
	s_mov_b32 s100, s60
	v_lshl_add_u64 v[128:129], v[126:127], 0, s[100:101]
	global_load_dwordx4 v[122:125], v[128:129], off nt
	s_barrier
	s_branch .LBB0_31

.LBB0_31:
	v_lshl_add_u64 v[32:33], v[30:31], 0, s[2:3]
	v_add_co_u32_e32 v6, vcc, s35, v32
	s_nop 0
	s_nop 0
	v_addc_co_u32_e32 v7, vcc, 0, v33, vcc
	v_add_co_u32_e32 v10, vcc, s57, v32
	s_nop 0
	s_nop 0
	v_addc_co_u32_e32 v11, vcc, 0, v33, vcc
	v_add_co_u32_e32 v14, vcc, s60, v32
	s_nop 0
	s_nop 0
	v_addc_co_u32_e32 v15, vcc, 0, v33, vcc
	s_nop 0
	v_mov_b32_e32 v16, s1
	ds_read2_b32 v[14:15], v16 offset1:8
	v_add_u32_e32 v66, 0x1000, v16
	v_add_u32_e32 v68, 0x1800, v16
	v_add_u32_e32 v70, 0x2000, v16
	v_add_u32_e32 v26, 0x800, v16
	ds_read2_b32 v[16:17], v16 offset0:16 offset1:24
	ds_read2_b32 v[56:57], v26 offset1:8
	ds_read2_b32 v[58:59], v66 offset1:8
	ds_read2_b32 v[60:61], v68 offset1:8
	ds_read2_b32 v[62:63], v70 offset1:8
	ds_read2_b32 v[64:65], v26 offset0:16 offset1:24
	ds_read2_b32 v[66:67], v66 offset0:16 offset1:24
	ds_read2_b32 v[68:69], v68 offset0:16 offset1:24
	ds_read2_b32 v[70:71], v70 offset0:16 offset1:24
	s_waitcnt lgkmcnt(9)
	v_mov_b32_e32 v26, v15
	s_waitcnt lgkmcnt(7)
	v_mov_b32_e32 v74, v57
	s_waitcnt lgkmcnt(6)
	v_mov_b32_e32 v76, v59
	s_waitcnt lgkmcnt(5)
	v_mov_b32_e32 v78, v61
	s_waitcnt lgkmcnt(4)
	v_mov_b32_e32 v80, v63
	v_mov_b32_e32 v72, v17
	s_waitcnt lgkmcnt(3)
	v_mov_b32_e32 v82, v65
	s_waitcnt lgkmcnt(2)
	v_mov_b32_e32 v84, v67
	s_waitcnt lgkmcnt(1)
	v_mov_b32_e32 v86, v69
	s_waitcnt lgkmcnt(0)
	v_mov_b32_e32 v88, v71
	s_cmp_eq_u32 s2, 0x2d00000
	s_mov_b64 s[4:5], -1
	s_waitcnt vmcnt(3)
	v_pk_fma_f32 v[22:23], v[110:111], v[14:15], v[22:23] op_sel_hi:[1,0,1]
	v_pk_fma_f32 v[14:15], v[112:113], v[14:15], v[24:25] op_sel_hi:[1,0,1]
	v_pk_fma_f32 v[24:25], v[110:111], v[56:57], v[42:43] op_sel_hi:[1,0,1]
	v_pk_fma_f32 v[36:37], v[112:113], v[56:57], v[36:37] op_sel_hi:[1,0,1]
	v_pk_fma_f32 v[42:43], v[110:111], v[58:59], v[46:47] op_sel_hi:[1,0,1]
	v_pk_fma_f32 v[38:39], v[112:113], v[58:59], v[38:39] op_sel_hi:[1,0,1]
	v_pk_fma_f32 v[46:47], v[110:111], v[60:61], v[48:49] op_sel_hi:[1,0,1]
	v_pk_fma_f32 v[40:41], v[112:113], v[60:61], v[40:41] op_sel_hi:[1,0,1]
	v_pk_fma_f32 v[2:3], v[110:111], v[62:63], v[50:51] op_sel_hi:[1,0,1]
	v_pk_fma_f32 v[4:5], v[112:113], v[62:63], v[44:45] op_sel_hi:[1,0,1]
	s_waitcnt vmcnt(2)
	v_pk_fma_f32 v[22:23], v[114:115], v[26:27], v[22:23] op_sel_hi:[1,0,1]
	v_pk_fma_f32 v[14:15], v[116:117], v[26:27], v[14:15] op_sel_hi:[1,0,1]
	v_pk_fma_f32 v[24:25], v[114:115], v[74:75], v[24:25] op_sel_hi:[1,0,1]
	v_pk_fma_f32 v[36:37], v[116:117], v[74:75], v[36:37] op_sel_hi:[1,0,1]
	v_pk_fma_f32 v[42:43], v[114:115], v[76:77], v[42:43] op_sel_hi:[1,0,1]
	v_pk_fma_f32 v[38:39], v[116:117], v[76:77], v[38:39] op_sel_hi:[1,0,1]
	v_pk_fma_f32 v[44:45], v[114:115], v[78:79], v[46:47] op_sel_hi:[1,0,1]
	v_pk_fma_f32 v[40:41], v[116:117], v[78:79], v[40:41] op_sel_hi:[1,0,1]
	v_pk_fma_f32 v[2:3], v[114:115], v[80:81], v[2:3] op_sel_hi:[1,0,1]
	v_pk_fma_f32 v[4:5], v[116:117], v[80:81], v[4:5] op_sel_hi:[1,0,1]
	s_waitcnt vmcnt(1)
	v_pk_fma_f32 v[6:7], v[120:121], v[16:17], v[14:15] op_sel_hi:[1,0,1]
	v_pk_fma_f32 v[8:9], v[118:119], v[16:17], v[22:23] op_sel_hi:[1,0,1]
	v_pk_fma_f32 v[14:15], v[120:121], v[64:65], v[36:37] op_sel_hi:[1,0,1]
	v_pk_fma_f32 v[16:17], v[118:119], v[64:65], v[24:25] op_sel_hi:[1,0,1]
	v_pk_fma_f32 v[22:23], v[120:121], v[66:67], v[38:39] op_sel_hi:[1,0,1]
	v_pk_fma_f32 v[24:25], v[118:119], v[66:67], v[42:43] op_sel_hi:[1,0,1]
	v_pk_fma_f32 v[36:37], v[120:121], v[68:69], v[40:41] op_sel_hi:[1,0,1]
	v_pk_fma_f32 v[38:39], v[118:119], v[68:69], v[44:45] op_sel_hi:[1,0,1]
	v_pk_fma_f32 v[40:41], v[120:121], v[70:71], v[4:5] op_sel_hi:[1,0,1]
	v_pk_fma_f32 v[42:43], v[118:119], v[70:71], v[2:3] op_sel_hi:[1,0,1]
	s_waitcnt vmcnt(0)
	v_pk_fma_f32 v[4:5], v[124:125], v[72:73], v[6:7] op_sel_hi:[1,0,1]
	v_pk_fma_f32 v[2:3], v[122:123], v[72:73], v[8:9] op_sel_hi:[1,0,1]
	v_pk_fma_f32 v[8:9], v[124:125], v[82:83], v[14:15] op_sel_hi:[1,0,1]
	v_pk_fma_f32 v[6:7], v[122:123], v[82:83], v[16:17] op_sel_hi:[1,0,1]
	v_pk_fma_f32 v[12:13], v[124:125], v[84:85], v[22:23] op_sel_hi:[1,0,1]
	v_pk_fma_f32 v[10:11], v[122:123], v[84:85], v[24:25] op_sel_hi:[1,0,1]
	v_pk_fma_f32 v[16:17], v[124:125], v[86:87], v[36:37] op_sel_hi:[1,0,1]
	v_pk_fma_f32 v[14:15], v[122:123], v[86:87], v[38:39] op_sel_hi:[1,0,1]
	v_pk_fma_f32 v[20:21], v[124:125], v[88:89], v[40:41] op_sel_hi:[1,0,1]
	v_pk_fma_f32 v[18:19], v[122:123], v[88:89], v[42:43] op_sel_hi:[1,0,1]
	s_cbranch_scc1 .LBB0_30
	v_add_co_u32_e32 v22, vcc, 0x300000, v32
	v_mov_b32_e32 v91, s1
	s_nop 0
	v_addc_co_u32_e32 v23, vcc, 0, v33, vcc
	v_add_co_u32_e32 v36, vcc, s61, v32
	global_load_dwordx4 v[22:25], v[22:23], off nt
	s_nop 0
	v_addc_co_u32_e32 v37, vcc, 0, v33, vcc
	v_add_co_u32_e32 v40, vcc, s63, v32
	global_load_dwordx4 v[36:39], v[36:37], off nt
	s_nop 0
	v_addc_co_u32_e32 v41, vcc, 0, v33, vcc
	v_add_co_u32_e32 v44, vcc, s66, v32
	global_load_dwordx4 v[40:43], v[40:41], off nt
	s_nop 0
	v_addc_co_u32_e32 v45, vcc, 0, v33, vcc
	global_load_dwordx4 v[44:47], v[44:45], off nt
	v_add_co_u32_e32 v48, vcc, s67, v32
	ds_read2_b32 v[68:69], v91 offset0:32 offset1:40
	s_nop 0
	v_addc_co_u32_e32 v49, vcc, 0, v33, vcc
	v_add_co_u32_e32 v56, vcc, s68, v32
	global_load_dwordx4 v[48:51], v[48:49], off nt
	s_nop 0
	v_addc_co_u32_e32 v57, vcc, 0, v33, vcc
	global_load_dwordx4 v[56:59], v[56:57], off nt
	v_add_co_u32_e32 v60, vcc, s69, v32
	ds_read2_b32 v[70:71], v91 offset0:48 offset1:56
	s_nop 0
	v_addc_co_u32_e32 v61, vcc, 0, v33, vcc
	v_add_co_u32_e32 v32, vcc, s70, v32
	v_add_u32_e32 v93, 0x800, v91
	s_nop 0
	v_addc_co_u32_e32 v33, vcc, 0, v33, vcc
	global_load_dwordx4 v[60:63], v[60:61], off nt
	s_nop 0
	global_load_dwordx4 v[64:67], v[32:33], off nt
	s_add_u32 s98, s2, 0x900000
	s_addc_u32 s99, s3, 0
	v_lshl_add_u64 v[126:127], v[30:31], 0, s[98:99]
	global_load_dwordx4 v[110:113], v[126:127], off nt
	s_mov_b32 s101, 0
	s_mov_b32 s100, s35
	v_lshl_add_u64 v[128:129], v[126:127], 0, s[100:101]
	global_load_dwordx4 v[114:117], v[128:129], off nt
	s_mov_b32 s100, s57
	v_lshl_add_u64 v[128:129], v[126:127], 0, s[100:101]
	global_load_dwordx4 v[118:121], v[128:129], off nt
	s_mov_b32 s100, s60
	v_lshl_add_u64 v[128:129], v[126:127], 0, s[100:101]
	global_load_dwordx4 v[122:125], v[128:129], off nt
	v_add_u32_e32 v102, 0x1000, v91
	v_add_u32_e32 v103, 0x1800, v91
	v_add_u32_e32 v104, 0x2000, v91
	ds_read2_b32 v[32:33], v93 offset0:32 offset1:40
	ds_read2_b32 v[72:73], v102 offset0:32 offset1:40
	ds_read2_b32 v[74:75], v103 offset0:32 offset1:40
	ds_read2_b32 v[76:77], v104 offset0:32 offset1:40
	ds_read2_b32 v[78:79], v93 offset0:48 offset1:56
	ds_read2_b32 v[80:81], v102 offset0:48 offset1:56
	ds_read2_b32 v[82:83], v103 offset0:48 offset1:56
	ds_read2_b32 v[84:85], v104 offset0:48 offset1:56
	s_waitcnt lgkmcnt(9)
	v_mov_b32_e32 v26, v69
	s_waitcnt lgkmcnt(7)
	v_mov_b32_e32 v86, v33
	s_waitcnt lgkmcnt(6)
	v_mov_b32_e32 v88, v73
	s_waitcnt lgkmcnt(5)
	v_mov_b32_e32 v90, v75
	s_waitcnt lgkmcnt(4)
	v_mov_b32_e32 v92, v77
	s_addk_i32 s1, 0x180
	s_add_u32 s2, s2, 0x900000
	s_addc_u32 s3, s3, 0
	s_mov_b64 s[4:5], 0
	s_waitcnt vmcnt(11)
	v_pk_fma_f32 v[94:95], v[24:25], v[68:69], v[4:5] op_sel_hi:[1,0,1]
	v_pk_fma_f32 v[68:69], v[22:23], v[68:69], v[2:3] op_sel_hi:[1,0,1]
	v_pk_fma_f32 v[96:97], v[24:25], v[32:33], v[8:9] op_sel_hi:[1,0,1]
	v_pk_fma_f32 v[32:33], v[22:23], v[32:33], v[6:7] op_sel_hi:[1,0,1]
	v_pk_fma_f32 v[98:99], v[24:25], v[72:73], v[12:13] op_sel_hi:[1,0,1]
	v_pk_fma_f32 v[72:73], v[22:23], v[72:73], v[10:11] op_sel_hi:[1,0,1]
	v_pk_fma_f32 v[100:101], v[24:25], v[74:75], v[16:17] op_sel_hi:[1,0,1]
	v_pk_fma_f32 v[74:75], v[22:23], v[74:75], v[14:15] op_sel_hi:[1,0,1]
	v_pk_fma_f32 v[24:25], v[24:25], v[76:77], v[20:21] op_sel_hi:[1,0,1]
	v_pk_fma_f32 v[22:23], v[22:23], v[76:77], v[18:19] op_sel_hi:[1,0,1]
	s_waitcnt vmcnt(10)
	v_pk_fma_f32 v[76:77], v[38:39], v[26:27], v[94:95] op_sel_hi:[1,0,1]
	v_pk_fma_f32 v[68:69], v[36:37], v[26:27], v[68:69] op_sel_hi:[1,0,1]
	v_pk_fma_f32 v[94:95], v[38:39], v[86:87], v[96:97] op_sel_hi:[1,0,1]
	v_pk_fma_f32 v[32:33], v[36:37], v[86:87], v[32:33] op_sel_hi:[1,0,1]
	v_pk_fma_f32 v[86:87], v[38:39], v[88:89], v[98:99] op_sel_hi:[1,0,1]
	v_pk_fma_f32 v[72:73], v[36:37], v[88:89], v[72:73] op_sel_hi:[1,0,1]
	v_pk_fma_f32 v[88:89], v[38:39], v[90:91], v[100:101] op_sel_hi:[1,0,1]
	v_pk_fma_f32 v[74:75], v[36:37], v[90:91], v[74:75] op_sel_hi:[1,0,1]
	v_pk_fma_f32 v[24:25], v[38:39], v[92:93], v[24:25] op_sel_hi:[1,0,1]
	v_pk_fma_f32 v[22:23], v[36:37], v[92:93], v[22:23] op_sel_hi:[1,0,1]
	s_waitcnt vmcnt(9)
	v_pk_fma_f32 v[36:37], v[42:43], v[70:71], v[76:77] op_sel_hi:[1,0,1]
	v_pk_fma_f32 v[38:39], v[40:41], v[70:71], v[68:69] op_sel_hi:[1,0,1]
	v_mov_b32_e32 v26, v71
	s_waitcnt lgkmcnt(3)
	v_pk_fma_f32 v[68:69], v[42:43], v[78:79], v[94:95] op_sel_hi:[1,0,1]
	v_pk_fma_f32 v[32:33], v[40:41], v[78:79], v[32:33] op_sel_hi:[1,0,1]
	s_waitcnt vmcnt(8)
	v_pk_fma_f32 v[36:37], v[46:47], v[26:27], v[36:37] op_sel_hi:[1,0,1]
	v_pk_fma_f32 v[38:39], v[44:45], v[26:27], v[38:39] op_sel_hi:[1,0,1]
	v_mov_b32_e32 v26, v79
	s_waitcnt lgkmcnt(2)
	v_pk_fma_f32 v[76:77], v[42:43], v[80:81], v[86:87] op_sel_hi:[1,0,1]
	v_pk_fma_f32 v[72:73], v[40:41], v[80:81], v[72:73] op_sel_hi:[1,0,1]
	s_waitcnt lgkmcnt(1)
	v_pk_fma_f32 v[74:75], v[40:41], v[82:83], v[74:75] op_sel_hi:[1,0,1]
	s_waitcnt lgkmcnt(0)
	v_pk_fma_f32 v[22:23], v[40:41], v[84:85], v[22:23] op_sel_hi:[1,0,1]
	v_pk_fma_f32 v[40:41], v[46:47], v[26:27], v[68:69] op_sel_hi:[1,0,1]
	v_pk_fma_f32 v[32:33], v[44:45], v[26:27], v[32:33] op_sel_hi:[1,0,1]
	v_mov_b32_e32 v26, v81
	v_pk_fma_f32 v[86:87], v[42:43], v[82:83], v[88:89] op_sel_hi:[1,0,1]
	v_pk_fma_f32 v[24:25], v[42:43], v[84:85], v[24:25] op_sel_hi:[1,0,1]
	v_pk_fma_f32 v[42:43], v[46:47], v[26:27], v[76:77] op_sel_hi:[1,0,1]
	v_pk_fma_f32 v[68:69], v[44:45], v[26:27], v[72:73] op_sel_hi:[1,0,1]
	v_mov_b32_e32 v26, v83
	v_pk_fma_f32 v[70:71], v[46:47], v[26:27], v[86:87] op_sel_hi:[1,0,1]
	v_pk_fma_f32 v[72:73], v[44:45], v[26:27], v[74:75] op_sel_hi:[1,0,1]
	ds_read2_b32 v[74:75], v91 offset0:64 offset1:72
	v_mov_b32_e32 v26, v85
	v_pk_fma_f32 v[24:25], v[46:47], v[26:27], v[24:25] op_sel_hi:[1,0,1]
	ds_read2_b32 v[46:47], v93 offset0:64 offset1:72
	v_pk_fma_f32 v[22:23], v[44:45], v[26:27], v[22:23] op_sel_hi:[1,0,1]
	ds_read2_b32 v[44:45], v102 offset0:64 offset1:72
	ds_read2_b32 v[76:77], v103 offset0:64 offset1:72
	ds_read2_b32 v[78:79], v104 offset0:64 offset1:72
	s_waitcnt vmcnt(7) lgkmcnt(4)
	v_pk_fma_f32 v[36:37], v[50:51], v[74:75], v[36:37] op_sel_hi:[1,0,1]
	v_pk_fma_f32 v[38:39], v[48:49], v[74:75], v[38:39] op_sel_hi:[1,0,1]
	v_mov_b32_e32 v26, v75
	s_waitcnt lgkmcnt(3)
	v_pk_fma_f32 v[40:41], v[50:51], v[46:47], v[40:41] op_sel_hi:[1,0,1]
	v_pk_fma_f32 v[32:33], v[48:49], v[46:47], v[32:33] op_sel_hi:[1,0,1]
	s_waitcnt vmcnt(6)
	v_pk_fma_f32 v[36:37], v[58:59], v[26:27], v[36:37] op_sel_hi:[1,0,1]
	v_pk_fma_f32 v[38:39], v[56:57], v[26:27], v[38:39] op_sel_hi:[1,0,1]
	v_mov_b32_e32 v26, v47
	s_waitcnt lgkmcnt(2)
	v_pk_fma_f32 v[42:43], v[50:51], v[44:45], v[42:43] op_sel_hi:[1,0,1]
	v_pk_fma_f32 v[68:69], v[48:49], v[44:45], v[68:69] op_sel_hi:[1,0,1]
	v_pk_fma_f32 v[40:41], v[58:59], v[26:27], v[40:41] op_sel_hi:[1,0,1]
	v_pk_fma_f32 v[32:33], v[56:57], v[26:27], v[32:33] op_sel_hi:[1,0,1]
	v_mov_b32_e32 v26, v45
	s_waitcnt lgkmcnt(1)
	v_pk_fma_f32 v[70:71], v[50:51], v[76:77], v[70:71] op_sel_hi:[1,0,1]
	v_pk_fma_f32 v[72:73], v[48:49], v[76:77], v[72:73] op_sel_hi:[1,0,1]
	v_pk_fma_f32 v[42:43], v[58:59], v[26:27], v[42:43] op_sel_hi:[1,0,1]
	v_pk_fma_f32 v[44:45], v[56:57], v[26:27], v[68:69] op_sel_hi:[1,0,1]
	v_mov_b32_e32 v26, v77
	s_waitcnt lgkmcnt(0)
	v_pk_fma_f32 v[24:25], v[50:51], v[78:79], v[24:25] op_sel_hi:[1,0,1]
	v_pk_fma_f32 v[22:23], v[48:49], v[78:79], v[22:23] op_sel_hi:[1,0,1]
	v_pk_fma_f32 v[46:47], v[58:59], v[26:27], v[70:71] op_sel_hi:[1,0,1]
	v_pk_fma_f32 v[48:49], v[56:57], v[26:27], v[72:73] op_sel_hi:[1,0,1]
	v_mov_b32_e32 v26, v79
	ds_read2_b32 v[50:51], v91 offset0:80 offset1:88
	v_pk_fma_f32 v[24:25], v[58:59], v[26:27], v[24:25] op_sel_hi:[1,0,1]
	ds_read2_b32 v[58:59], v93 offset0:80 offset1:88
	v_pk_fma_f32 v[22:23], v[56:57], v[26:27], v[22:23] op_sel_hi:[1,0,1]
	ds_read2_b32 v[56:57], v102 offset0:80 offset1:88
	ds_read2_b32 v[68:69], v103 offset0:80 offset1:88
	ds_read2_b32 v[70:71], v104 offset0:80 offset1:88
	s_waitcnt vmcnt(5) lgkmcnt(4)
	v_pk_fma_f32 v[36:37], v[62:63], v[50:51], v[36:37] op_sel_hi:[1,0,1]
	v_pk_fma_f32 v[38:39], v[60:61], v[50:51], v[38:39] op_sel_hi:[1,0,1]
	s_waitcnt lgkmcnt(3)
	v_pk_fma_f32 v[40:41], v[62:63], v[58:59], v[40:41] op_sel_hi:[1,0,1]
	v_pk_fma_f32 v[32:33], v[60:61], v[58:59], v[32:33] op_sel_hi:[1,0,1]
	s_waitcnt lgkmcnt(2)
	v_pk_fma_f32 v[44:45], v[60:61], v[56:57], v[44:45] op_sel_hi:[1,0,1]
	s_waitcnt lgkmcnt(1)
	v_pk_fma_f32 v[48:49], v[60:61], v[68:69], v[48:49] op_sel_hi:[1,0,1]
	s_waitcnt lgkmcnt(0)
	v_pk_fma_f32 v[60:61], v[60:61], v[70:71], v[22:23] op_sel_hi:[1,0,1]
	v_mov_b32_e32 v22, v51
	v_mov_b32_e32 v26, v59
	v_pk_fma_f32 v[72:73], v[62:63], v[56:57], v[42:43] op_sel_hi:[1,0,1]
	v_pk_fma_f32 v[74:75], v[62:63], v[68:69], v[46:47] op_sel_hi:[1,0,1]
	v_pk_fma_f32 v[62:63], v[62:63], v[70:71], v[24:25] op_sel_hi:[1,0,1]
	s_waitcnt vmcnt(4)
	v_pk_fma_f32 v[24:25], v[66:67], v[22:23], v[36:37] op_sel_hi:[1,0,1]
	v_pk_fma_f32 v[36:37], v[66:67], v[26:27], v[40:41] op_sel_hi:[1,0,1]
	v_pk_fma_f32 v[42:43], v[64:65], v[26:27], v[32:33] op_sel_hi:[1,0,1]
	v_mov_b32_e32 v26, v57
	v_pk_fma_f32 v[22:23], v[64:65], v[22:23], v[38:39] op_sel_hi:[1,0,1]
	v_pk_fma_f32 v[38:39], v[66:67], v[26:27], v[72:73] op_sel_hi:[1,0,1]
	v_pk_fma_f32 v[46:47], v[64:65], v[26:27], v[44:45] op_sel_hi:[1,0,1]
	v_mov_b32_e32 v26, v69
	v_pk_fma_f32 v[40:41], v[66:67], v[26:27], v[74:75] op_sel_hi:[1,0,1]
	v_pk_fma_f32 v[48:49], v[64:65], v[26:27], v[48:49] op_sel_hi:[1,0,1]
	v_mov_b32_e32 v26, v71
	v_pk_fma_f32 v[44:45], v[66:67], v[26:27], v[62:63] op_sel_hi:[1,0,1]
	v_pk_fma_f32 v[50:51], v[64:65], v[26:27], v[60:61] op_sel_hi:[1,0,1]
	s_branch .LBB0_30
